# v15: first grid barrier census: 16 per-XCC counter loads issued together instead of one round trip each
# speedup vs baseline: 1.0020x; 1.0020x over previous
; __device__ __forceinline__ unsigned xb_ld(unsigned* p)              { return __hip_atomic_load(p, __ATOMIC_RELAXED, __HIP_MEMORY_SCOPE_AGENT); }
; __device__ __forceinline__ void xcd_barrier_complete(unsigned* bar, unsigned x, unsigned& nloc, unsigned& nx) {
;     ...
;     for (;;) {
;         sum = 0u; cnt = 0u; mine = 0u;
; #pragma unroll
;         for (unsigned j = 0; j < 16; ++j) { const unsigned c = xb_ld(&bar[XB_XCNT(j)]); sum += c; cnt += (c > 0u) ? 1u : 0u; mine = (j == x) ? c : mine; }
;         if (sum == G) break;
;         __builtin_amdgcn_s_sleep(1);
;         if ((++sp & 255u) == 0u) { if (xb_ld(&bar[XB_TMO])) break; if (sp > XB_SPIN_CAP) { atomicAdd(&bar[XB_TMO], 1u); break; } }
;     }
.LBB0_966:
	s_waitcnt lgkmcnt(0)
	global_load_dword v4, v1, s[60:61] sc1
	global_load_dword v0, v1, s[60:61] offset:256 sc1
	global_load_dword v2, v1, s[60:61] offset:512 sc1
	global_load_dword v3, v1, s[60:61] offset:768 sc1
	global_load_dword v5, v1, s[60:61] offset:1024 sc1
	global_load_dword v6, v1, s[60:61] offset:1280 sc1
	global_load_dword v7, v1, s[60:61] offset:1536 sc1
	global_load_dword v8, v1, s[60:61] offset:1792 sc1
	global_load_dword v9, v1, s[60:61] offset:2048 sc1
	global_load_dword v10, v1, s[60:61] offset:2304 sc1
	global_load_dword v11, v1, s[60:61] offset:2560 sc1
	global_load_dword v12, v1, s[60:61] offset:2816 sc1
	global_load_dword v13, v1, s[60:61] offset:3072 sc1
	global_load_dword v14, v1, s[60:61] offset:3328 sc1
	global_load_dword v15, v1, s[60:61] offset:3584 sc1
	global_load_dword v16, v1, s[60:61] offset:3840 sc1
	s_mov_b64 s[6:7], -1
	s_mov_b64 s[4:5], -1
	s_waitcnt vmcnt(0)
	v_add_u32_e32 v17, v0, v4
	v_add_u32_e32 v17, v17, v2
	v_add_u32_e32 v17, v17, v3
	v_add_u32_e32 v17, v17, v5
	v_add_u32_e32 v17, v17, v6
	v_add_u32_e32 v17, v17, v7
	v_add_u32_e32 v17, v17, v8
	v_add_u32_e32 v17, v17, v9
	v_add_u32_e32 v17, v17, v10
	v_add_u32_e32 v17, v17, v11
	v_add_u32_e32 v17, v17, v12
	v_add_u32_e32 v17, v17, v13
	v_add_u32_e32 v17, v17, v14
	v_add_u32_e32 v17, v17, v15
	v_add_u32_e32 v17, v17, v16
	v_cmp_eq_u32_e32 vcc, s91, v17
	s_cbranch_vccnz .LBB0_965
	s_and_b32 s4, s2, 0xff
	s_cmp_eq_u32 s4, 0
	s_mov_b64 s[4:5], -1
	s_mov_b64 s[8:9], -1
	s_sleep 1
	s_cbranch_scc1 .LBB0_970
	s_and_b64 vcc, exec, s[8:9]
	s_cbranch_vccz .LBB0_965
